# phase 0 norm1: four rows per wave in flight (DPP reduction); gw read before the gain loads (fixes the intermittent fault of v113)
# baseline (speedup 1.0000x reference)
.LBB0_145:
	s_load_dwordx16 s[36:51], s[88:89], 0x0
	s_lshl_b32 s0, s2, 2
	v_writelane_b32 v238, s0, 37
	v_add_u32_e32 v20, s0, v0
	s_movk_i32 s0, 0x4280
	v_cmp_gt_i32_e32 vcc, s0, v20
	v_lshlrev_b32_e32 v157, 2, v153
	v_mbcnt_lo_u32_b32 v156, -1, 0
	s_and_saveexec_b64 s[6:7], vcc
	s_cbranch_execz .LBB0_156
	s_cmp_eq_u32 s3, 0x200
	s_cbranch_scc1 .Lrn0_entry
	v_and_b32_e32 v16, 0xfc, v157
	v_lshlrev_b32_e32 v12, 2, v16
	s_waitcnt lgkmcnt(0)
	global_load_dwordx4 v[0:3], v12, s[50:51]
	global_load_dwordx4 v[4:7], v12, s[50:51] offset:1024
	global_load_dwordx4 v[8:11], v12, s[50:51] offset:2048
	s_nop 0
	global_load_dwordx4 v[12:15], v12, s[50:51] offset:3072
	v_mbcnt_hi_u32_b32 v18, -1, v156
	v_and_b32_e32 v19, 64, v18
	v_add_u32_e32 v19, 64, v19
	v_xor_b32_e32 v21, 32, v18
	v_cmp_lt_i32_e32 vcc, v21, v19
	s_load_dword s0, s[14:15], 0x10
	s_load_dword s3, s[14:15], 0x0
	v_cndmask_b32_e32 v21, v18, v21, vcc
	v_lshlrev_b32_e32 v28, 2, v21
	v_xor_b32_e32 v21, 16, v18
	v_cmp_lt_i32_e32 vcc, v21, v19
	s_waitcnt lgkmcnt(0)
	s_lshr_b32 s0, s0, 16
	s_cmp_lg_u32 s0, 0
	v_cndmask_b32_e32 v21, v18, v21, vcc
	v_lshlrev_b32_e32 v29, 2, v21
	v_xor_b32_e32 v21, 8, v18
	v_cmp_lt_i32_e32 vcc, v21, v19
	s_cselect_b64 s[0:1], -1, 0
	s_cmp_lg_u64 s[0:1], 0
	v_cndmask_b32_e32 v21, v18, v21, vcc
	v_lshlrev_b32_e32 v30, 2, v21
	v_xor_b32_e32 v21, 4, v18
	v_cmp_lt_i32_e32 vcc, v21, v19
	s_addc_u32 s0, s3, 0
	s_lshl_b32 s8, s0, 2
	v_cndmask_b32_e32 v21, v18, v21, vcc
	v_lshlrev_b32_e32 v31, 2, v21
	v_xor_b32_e32 v21, 2, v18
	v_cmp_lt_i32_e32 vcc, v21, v19
	v_mov_b32_e32 v17, 0
	s_mov_b64 s[0:1], 0x8ba0000
	v_cndmask_b32_e32 v21, v18, v21, vcc
	v_lshlrev_b32_e32 v32, 2, v21
	v_xor_b32_e32 v21, 1, v18
	v_cmp_lt_i32_e32 vcc, v21, v19
	s_ashr_i32 s9, s8, 31
	s_lshl_b64 s[10:11], s[8:9], 11
	v_cndmask_b32_e32 v18, v18, v21, vcc
	v_ashrrev_i32_e32 v21, 31, v20
	v_lshlrev_b32_e32 v33, 2, v18
	v_add_u32_e32 v18, 0xffffbf80, v20
	v_lshlrev_b64 v[20:21], 11, v[20:21]
	v_lshl_or_b32 v20, v152, 3, v20
	v_lshl_add_u64 v[20:21], s[30:31], 0, v[20:21]
	v_lshl_add_u64 v[20:21], v[20:21], 0, s[0:1]
	s_mov_b64 s[12:13], 0
	s_movk_i32 s3, 0x407f
	s_mov_b32 s9, 0xfe03f81
	s_movk_i32 s14, 0xf7f0
	v_lshlrev_b32_e32 v22, 2, v16
	v_mov_b32_e32 v23, v17
	v_mov_b32_e32 v34, 0x358637bd
	s_mov_b32 s15, 0x800000
	s_movk_i32 s33, 0x427f
	s_branch .LBB0_149

.Lrn0_entry:
	s_waitcnt lgkmcnt(0)
	v_readfirstlane_b32 s3, v20
	v_lshlrev_b32_e32 v4, 4, v152
	v_lshlrev_b32_e32 v5, 3, v152
	v_mov_b32_e32 v7, 0x358637bd
	s_nop 3
	global_load_dwordx4 v[8:11], v4, s[50:51]
	global_load_dwordx4 v[12:15], v4, s[50:51] offset:1024
	global_load_dwordx4 v[16:19], v4, s[50:51] offset:2048
	global_load_dwordx4 v[20:23], v4, s[50:51] offset:3072
	s_lshl_b32 s10, s3, 3
	s_lshl_b32 s34, s3, 2
	s_addk_i32 s34, 0x4000
	s_cmp_lt_u32 s3, 0xa0
	s_cselect_b32 s4, 3, 2
	s_mov_b32 s11, 0
.Lrn0_grp:
	s_add_i32 s12, s10, 0
	s_cmpk_lt_i32 s12, 0x4080
	s_cbranch_scc1 .Lrn0_p0
	s_sub_i32 s13, s12, 0x4080
	s_lshl_b32 s13, s13, 12
	s_add_u32 s52, s38, s13
	s_addc_u32 s53, s39, 0
	s_branch .Lrn0_l0
.Lrn0_p0:
	s_mul_hi_u32 s13, s12, 0xfe03f81
	s_lshr_b32 s13, s13, 7
	s_mul_i32 s14, s13, 0x810
	s_sub_i32 s14, s12, s14
	s_cmp_lt_u32 s14, 16
	s_cbranch_scc0 .Lrn0_x0
	s_lshl_b32 s14, s14, 12
	s_add_u32 s52, s48, s14
	s_addc_u32 s53, s49, 0
	s_branch .Lrn0_l0
.Lrn0_x0:
	s_sub_i32 s14, s14, 16
	s_lshl_b32 s14, s14, 12
	s_lshl_b32 s13, s13, 23
	s_add_u32 s14, s14, s13
	s_add_u32 s52, s36, s14
	s_addc_u32 s53, s37, 0
.Lrn0_l0:
	global_load_dwordx4 v[32:35], v4, s[52:53]
	global_load_dwordx4 v[36:39], v4, s[52:53] offset:1024
	global_load_dwordx4 v[40:43], v4, s[52:53] offset:2048
	global_load_dwordx4 v[44:47], v4, s[52:53] offset:3072
	s_add_i32 s12, s10, 1
	s_cmpk_lt_i32 s12, 0x4080
	s_cbranch_scc1 .Lrn0_p1
	s_sub_i32 s13, s12, 0x4080
	s_lshl_b32 s13, s13, 12
	s_add_u32 s54, s38, s13
	s_addc_u32 s55, s39, 0
	s_branch .Lrn0_l1
.Lrn0_p1:
	s_mul_hi_u32 s13, s12, 0xfe03f81
	s_lshr_b32 s13, s13, 7
	s_mul_i32 s14, s13, 0x810
	s_sub_i32 s14, s12, s14
	s_cmp_lt_u32 s14, 16
	s_cbranch_scc0 .Lrn0_x1
	s_lshl_b32 s14, s14, 12
	s_add_u32 s54, s48, s14
	s_addc_u32 s55, s49, 0
	s_branch .Lrn0_l1
.Lrn0_x1:
	s_sub_i32 s14, s14, 16
	s_lshl_b32 s14, s14, 12
	s_lshl_b32 s13, s13, 23
	s_add_u32 s14, s14, s13
	s_add_u32 s54, s36, s14
	s_addc_u32 s55, s37, 0
.Lrn0_l1:
	global_load_dwordx4 v[48:51], v4, s[54:55]
	global_load_dwordx4 v[52:55], v4, s[54:55] offset:1024
	global_load_dwordx4 v[56:59], v4, s[54:55] offset:2048
	global_load_dwordx4 v[60:63], v4, s[54:55] offset:3072
	s_add_i32 s12, s10, 2
	s_cmpk_lt_i32 s12, 0x4080
	s_cbranch_scc1 .Lrn0_p2
	s_sub_i32 s13, s12, 0x4080
	s_lshl_b32 s13, s13, 12
	s_add_u32 s56, s38, s13
	s_addc_u32 s57, s39, 0
	s_branch .Lrn0_l2
.Lrn0_p2:
	s_mul_hi_u32 s13, s12, 0xfe03f81
	s_lshr_b32 s13, s13, 7
	s_mul_i32 s14, s13, 0x810
	s_sub_i32 s14, s12, s14
	s_cmp_lt_u32 s14, 16
	s_cbranch_scc0 .Lrn0_x2
	s_lshl_b32 s14, s14, 12
	s_add_u32 s56, s48, s14
	s_addc_u32 s57, s49, 0
	s_branch .Lrn0_l2
.Lrn0_x2:
	s_sub_i32 s14, s14, 16
	s_lshl_b32 s14, s14, 12
	s_lshl_b32 s13, s13, 23
	s_add_u32 s14, s14, s13
	s_add_u32 s56, s36, s14
	s_addc_u32 s57, s37, 0
.Lrn0_l2:
	global_load_dwordx4 v[64:67], v4, s[56:57]
	global_load_dwordx4 v[68:71], v4, s[56:57] offset:1024
	global_load_dwordx4 v[72:75], v4, s[56:57] offset:2048
	global_load_dwordx4 v[76:79], v4, s[56:57] offset:3072
	s_add_i32 s12, s10, 3
	s_cmpk_lt_i32 s12, 0x4080
	s_cbranch_scc1 .Lrn0_p3
	s_sub_i32 s13, s12, 0x4080
	s_lshl_b32 s13, s13, 12
	s_add_u32 s58, s38, s13
	s_addc_u32 s59, s39, 0
	s_branch .Lrn0_l3
.Lrn0_p3:
	s_mul_hi_u32 s13, s12, 0xfe03f81
	s_lshr_b32 s13, s13, 7
	s_mul_i32 s14, s13, 0x810
	s_sub_i32 s14, s12, s14
	s_cmp_lt_u32 s14, 16
	s_cbranch_scc0 .Lrn0_x3
	s_lshl_b32 s14, s14, 12
	s_add_u32 s58, s48, s14
	s_addc_u32 s59, s49, 0
	s_branch .Lrn0_l3
.Lrn0_x3:
	s_sub_i32 s14, s14, 16
	s_lshl_b32 s14, s14, 12
	s_lshl_b32 s13, s13, 23
	s_add_u32 s14, s14, s13
	s_add_u32 s58, s36, s14
	s_addc_u32 s59, s37, 0
.Lrn0_l3:
	global_load_dwordx4 v[80:83], v4, s[58:59]
	global_load_dwordx4 v[84:87], v4, s[58:59] offset:1024
	global_load_dwordx4 v[88:91], v4, s[58:59] offset:2048
	global_load_dwordx4 v[92:95], v4, s[58:59] offset:3072
	s_waitcnt vmcnt(0)
	v_pk_mul_f32 v[24:25], v[32:33], v[32:33]
	v_pk_mul_f32 v[26:27], v[48:49], v[48:49]
	v_pk_mul_f32 v[28:29], v[64:65], v[64:65]
	v_pk_mul_f32 v[30:31], v[80:81], v[80:81]
	v_pk_fma_f32 v[24:25], v[34:35], v[34:35], v[24:25]
	v_pk_fma_f32 v[26:27], v[50:51], v[50:51], v[26:27]
	v_pk_fma_f32 v[28:29], v[66:67], v[66:67], v[28:29]
	v_pk_fma_f32 v[30:31], v[82:83], v[82:83], v[30:31]
	v_pk_fma_f32 v[24:25], v[36:37], v[36:37], v[24:25]
	v_pk_fma_f32 v[26:27], v[52:53], v[52:53], v[26:27]
	v_pk_fma_f32 v[28:29], v[68:69], v[68:69], v[28:29]
	v_pk_fma_f32 v[30:31], v[84:85], v[84:85], v[30:31]
	v_pk_fma_f32 v[24:25], v[38:39], v[38:39], v[24:25]
	v_pk_fma_f32 v[26:27], v[54:55], v[54:55], v[26:27]
	v_pk_fma_f32 v[28:29], v[70:71], v[70:71], v[28:29]
	v_pk_fma_f32 v[30:31], v[86:87], v[86:87], v[30:31]
	v_pk_fma_f32 v[24:25], v[40:41], v[40:41], v[24:25]
	v_pk_fma_f32 v[26:27], v[56:57], v[56:57], v[26:27]
	v_pk_fma_f32 v[28:29], v[72:73], v[72:73], v[28:29]
	v_pk_fma_f32 v[30:31], v[88:89], v[88:89], v[30:31]
	v_pk_fma_f32 v[24:25], v[42:43], v[42:43], v[24:25]
	v_pk_fma_f32 v[26:27], v[58:59], v[58:59], v[26:27]
	v_pk_fma_f32 v[28:29], v[74:75], v[74:75], v[28:29]
	v_pk_fma_f32 v[30:31], v[90:91], v[90:91], v[30:31]
	v_pk_fma_f32 v[24:25], v[44:45], v[44:45], v[24:25]
	v_pk_fma_f32 v[26:27], v[60:61], v[60:61], v[26:27]
	v_pk_fma_f32 v[28:29], v[76:77], v[76:77], v[28:29]
	v_pk_fma_f32 v[30:31], v[92:93], v[92:93], v[30:31]
	v_pk_fma_f32 v[24:25], v[46:47], v[46:47], v[24:25]
	v_pk_fma_f32 v[26:27], v[62:63], v[62:63], v[26:27]
	v_pk_fma_f32 v[28:29], v[78:79], v[78:79], v[28:29]
	v_pk_fma_f32 v[30:31], v[94:95], v[94:95], v[30:31]
	v_add_f32_e32 v24, v24, v25
	v_add_f32_e32 v26, v26, v27
	v_add_f32_e32 v28, v28, v29
	v_add_f32_e32 v30, v30, v31
	v_add_f32_dpp v24, v24, v24 quad_perm:[1,0,3,2] row_mask:0xf bank_mask:0xf bound_ctrl:1
	v_add_f32_dpp v26, v26, v26 quad_perm:[1,0,3,2] row_mask:0xf bank_mask:0xf bound_ctrl:1
	v_add_f32_dpp v28, v28, v28 quad_perm:[1,0,3,2] row_mask:0xf bank_mask:0xf bound_ctrl:1
	v_add_f32_dpp v30, v30, v30 quad_perm:[1,0,3,2] row_mask:0xf bank_mask:0xf bound_ctrl:1
	v_add_f32_dpp v24, v24, v24 quad_perm:[2,3,0,1] row_mask:0xf bank_mask:0xf bound_ctrl:1
	v_add_f32_dpp v26, v26, v26 quad_perm:[2,3,0,1] row_mask:0xf bank_mask:0xf bound_ctrl:1
	v_add_f32_dpp v28, v28, v28 quad_perm:[2,3,0,1] row_mask:0xf bank_mask:0xf bound_ctrl:1
	v_add_f32_dpp v30, v30, v30 quad_perm:[2,3,0,1] row_mask:0xf bank_mask:0xf bound_ctrl:1
	v_add_f32_dpp v24, v24, v24 row_half_mirror row_mask:0xf bank_mask:0xf bound_ctrl:1
	v_add_f32_dpp v26, v26, v26 row_half_mirror row_mask:0xf bank_mask:0xf bound_ctrl:1
	v_add_f32_dpp v28, v28, v28 row_half_mirror row_mask:0xf bank_mask:0xf bound_ctrl:1
	v_add_f32_dpp v30, v30, v30 row_half_mirror row_mask:0xf bank_mask:0xf bound_ctrl:1
	v_add_f32_dpp v24, v24, v24 row_mirror row_mask:0xf bank_mask:0xf bound_ctrl:1
	v_add_f32_dpp v26, v26, v26 row_mirror row_mask:0xf bank_mask:0xf bound_ctrl:1
	v_add_f32_dpp v28, v28, v28 row_mirror row_mask:0xf bank_mask:0xf bound_ctrl:1
	v_add_f32_dpp v30, v30, v30 row_mirror row_mask:0xf bank_mask:0xf bound_ctrl:1
	v_add_f32_dpp v24, v24, v24 row_bcast:15 row_mask:0xa bank_mask:0xf
	v_add_f32_dpp v26, v26, v26 row_bcast:15 row_mask:0xa bank_mask:0xf
	v_add_f32_dpp v28, v28, v28 row_bcast:15 row_mask:0xa bank_mask:0xf
	v_add_f32_dpp v30, v30, v30 row_bcast:15 row_mask:0xa bank_mask:0xf
	v_add_f32_dpp v24, v24, v24 row_bcast:31 row_mask:0xc bank_mask:0xf
	v_add_f32_dpp v26, v26, v26 row_bcast:31 row_mask:0xc bank_mask:0xf
	v_add_f32_dpp v28, v28, v28 row_bcast:31 row_mask:0xc bank_mask:0xf
	v_add_f32_dpp v30, v30, v30 row_bcast:31 row_mask:0xc bank_mask:0xf
	s_nop 1
	v_readlane_b32 s0, v24, 63
	v_readlane_b32 s1, v26, 63
	v_readlane_b32 s8, v28, 63
	v_readlane_b32 s9, v30, 63
	s_nop 3
	v_mov_b32_e32 v24, s0
	v_mov_b32_e32 v26, s1
	v_mov_b32_e32 v28, s8
	v_mov_b32_e32 v30, s9
	v_fmamk_f32 v24, v24, 0x3a800000, v7
	v_fmamk_f32 v26, v26, 0x3a800000, v7
	v_fmamk_f32 v28, v28, 0x3a800000, v7
	v_fmamk_f32 v30, v30, 0x3a800000, v7
	v_rsq_f32_e32 v24, v24
	v_rsq_f32_e32 v26, v26
	v_rsq_f32_e32 v28, v28
	v_rsq_f32_e32 v30, v30
	s_nop 1
	v_pk_mul_f32 v[32:33], v[32:33], v[24:25] op_sel_hi:[1,0]
	v_pk_mul_f32 v[34:35], v[34:35], v[24:25] op_sel_hi:[1,0]
	v_pk_mul_f32 v[36:37], v[36:37], v[24:25] op_sel_hi:[1,0]
	v_pk_mul_f32 v[38:39], v[38:39], v[24:25] op_sel_hi:[1,0]
	v_pk_mul_f32 v[40:41], v[40:41], v[24:25] op_sel_hi:[1,0]
	v_pk_mul_f32 v[42:43], v[42:43], v[24:25] op_sel_hi:[1,0]
	v_pk_mul_f32 v[44:45], v[44:45], v[24:25] op_sel_hi:[1,0]
	v_pk_mul_f32 v[46:47], v[46:47], v[24:25] op_sel_hi:[1,0]
	v_pk_mul_f32 v[48:49], v[48:49], v[26:27] op_sel_hi:[1,0]
	v_pk_mul_f32 v[50:51], v[50:51], v[26:27] op_sel_hi:[1,0]
	v_pk_mul_f32 v[52:53], v[52:53], v[26:27] op_sel_hi:[1,0]
	v_pk_mul_f32 v[54:55], v[54:55], v[26:27] op_sel_hi:[1,0]
	v_pk_mul_f32 v[56:57], v[56:57], v[26:27] op_sel_hi:[1,0]
	v_pk_mul_f32 v[58:59], v[58:59], v[26:27] op_sel_hi:[1,0]
	v_pk_mul_f32 v[60:61], v[60:61], v[26:27] op_sel_hi:[1,0]
	v_pk_mul_f32 v[62:63], v[62:63], v[26:27] op_sel_hi:[1,0]
	v_pk_mul_f32 v[64:65], v[64:65], v[28:29] op_sel_hi:[1,0]
	v_pk_mul_f32 v[66:67], v[66:67], v[28:29] op_sel_hi:[1,0]
	v_pk_mul_f32 v[68:69], v[68:69], v[28:29] op_sel_hi:[1,0]
	v_pk_mul_f32 v[70:71], v[70:71], v[28:29] op_sel_hi:[1,0]
	v_pk_mul_f32 v[72:73], v[72:73], v[28:29] op_sel_hi:[1,0]
	v_pk_mul_f32 v[74:75], v[74:75], v[28:29] op_sel_hi:[1,0]
	v_pk_mul_f32 v[76:77], v[76:77], v[28:29] op_sel_hi:[1,0]
	v_pk_mul_f32 v[78:79], v[78:79], v[28:29] op_sel_hi:[1,0]
	v_pk_mul_f32 v[80:81], v[80:81], v[30:31] op_sel_hi:[1,0]
	v_pk_mul_f32 v[82:83], v[82:83], v[30:31] op_sel_hi:[1,0]
	v_pk_mul_f32 v[84:85], v[84:85], v[30:31] op_sel_hi:[1,0]
	v_pk_mul_f32 v[86:87], v[86:87], v[30:31] op_sel_hi:[1,0]
	v_pk_mul_f32 v[88:89], v[88:89], v[30:31] op_sel_hi:[1,0]
	v_pk_mul_f32 v[90:91], v[90:91], v[30:31] op_sel_hi:[1,0]
	v_pk_mul_f32 v[92:93], v[92:93], v[30:31] op_sel_hi:[1,0]
	v_pk_mul_f32 v[94:95], v[94:95], v[30:31] op_sel_hi:[1,0]
	v_pk_mul_f32 v[32:33], v[32:33], v[8:9]
	v_pk_mul_f32 v[34:35], v[34:35], v[10:11]
	v_pk_mul_f32 v[36:37], v[36:37], v[12:13]
	v_pk_mul_f32 v[38:39], v[38:39], v[14:15]
	v_pk_mul_f32 v[40:41], v[40:41], v[16:17]
	v_pk_mul_f32 v[42:43], v[42:43], v[18:19]
	v_pk_mul_f32 v[44:45], v[44:45], v[20:21]
	v_pk_mul_f32 v[46:47], v[46:47], v[22:23]
	v_pk_mul_f32 v[48:49], v[48:49], v[8:9]
	v_pk_mul_f32 v[50:51], v[50:51], v[10:11]
	v_pk_mul_f32 v[52:53], v[52:53], v[12:13]
	v_pk_mul_f32 v[54:55], v[54:55], v[14:15]
	v_pk_mul_f32 v[56:57], v[56:57], v[16:17]
	v_pk_mul_f32 v[58:59], v[58:59], v[18:19]
	v_pk_mul_f32 v[60:61], v[60:61], v[20:21]
	v_pk_mul_f32 v[62:63], v[62:63], v[22:23]
	v_pk_mul_f32 v[64:65], v[64:65], v[8:9]
	v_pk_mul_f32 v[66:67], v[66:67], v[10:11]
	v_pk_mul_f32 v[68:69], v[68:69], v[12:13]
	v_pk_mul_f32 v[70:71], v[70:71], v[14:15]
	v_pk_mul_f32 v[72:73], v[72:73], v[16:17]
	v_pk_mul_f32 v[74:75], v[74:75], v[18:19]
	v_pk_mul_f32 v[76:77], v[76:77], v[20:21]
	v_pk_mul_f32 v[78:79], v[78:79], v[22:23]
	v_pk_mul_f32 v[80:81], v[80:81], v[8:9]
	v_pk_mul_f32 v[82:83], v[82:83], v[10:11]
	v_pk_mul_f32 v[84:85], v[84:85], v[12:13]
	v_pk_mul_f32 v[86:87], v[86:87], v[14:15]
	v_pk_mul_f32 v[88:89], v[88:89], v[16:17]
	v_pk_mul_f32 v[90:91], v[90:91], v[18:19]
	v_pk_mul_f32 v[92:93], v[92:93], v[20:21]
	v_pk_mul_f32 v[94:95], v[94:95], v[22:23]
	s_add_i32 s12, s10, 0
	s_lshl_b32 s13, s12, 11
	s_add_u32 s60, s30, 0x8ba0000
	s_addc_u32 s61, s31, 0
	s_add_u32 s60, s60, s13
	s_addc_u32 s61, s61, 0
	v_cvt_pk_f16_f32 v32, v32, v33
	v_cvt_pk_f16_f32 v33, v34, v35
	v_cvt_pk_f16_f32 v34, v36, v37
	v_cvt_pk_f16_f32 v35, v38, v39
	v_cvt_pk_f16_f32 v36, v40, v41
	v_cvt_pk_f16_f32 v37, v42, v43
	v_cvt_pk_f16_f32 v38, v44, v45
	v_cvt_pk_f16_f32 v39, v46, v47
	s_nop 0
	global_store_dwordx2 v5, v[32:33], s[60:61]
	global_store_dwordx2 v5, v[34:35], s[60:61] offset:512
	global_store_dwordx2 v5, v[36:37], s[60:61] offset:1024
	global_store_dwordx2 v5, v[38:39], s[60:61] offset:1536
	s_add_i32 s12, s10, 1
	s_lshl_b32 s13, s12, 11
	s_add_u32 s60, s30, 0x8ba0000
	s_addc_u32 s61, s31, 0
	s_add_u32 s60, s60, s13
	s_addc_u32 s61, s61, 0
	v_cvt_pk_f16_f32 v48, v48, v49
	v_cvt_pk_f16_f32 v49, v50, v51
	v_cvt_pk_f16_f32 v50, v52, v53
	v_cvt_pk_f16_f32 v51, v54, v55
	v_cvt_pk_f16_f32 v52, v56, v57
	v_cvt_pk_f16_f32 v53, v58, v59
	v_cvt_pk_f16_f32 v54, v60, v61
	v_cvt_pk_f16_f32 v55, v62, v63
	s_nop 0
	global_store_dwordx2 v5, v[48:49], s[60:61]
	global_store_dwordx2 v5, v[50:51], s[60:61] offset:512
	global_store_dwordx2 v5, v[52:53], s[60:61] offset:1024
	global_store_dwordx2 v5, v[54:55], s[60:61] offset:1536
	s_add_i32 s12, s10, 2
	s_lshl_b32 s13, s12, 11
	s_add_u32 s60, s30, 0x8ba0000
	s_addc_u32 s61, s31, 0
	s_add_u32 s60, s60, s13
	s_addc_u32 s61, s61, 0
	v_cvt_pk_f16_f32 v64, v64, v65
	v_cvt_pk_f16_f32 v65, v66, v67
	v_cvt_pk_f16_f32 v66, v68, v69
	v_cvt_pk_f16_f32 v67, v70, v71
	v_cvt_pk_f16_f32 v68, v72, v73
	v_cvt_pk_f16_f32 v69, v74, v75
	v_cvt_pk_f16_f32 v70, v76, v77
	v_cvt_pk_f16_f32 v71, v78, v79
	s_nop 0
	global_store_dwordx2 v5, v[64:65], s[60:61]
	global_store_dwordx2 v5, v[66:67], s[60:61] offset:512
	global_store_dwordx2 v5, v[68:69], s[60:61] offset:1024
	global_store_dwordx2 v5, v[70:71], s[60:61] offset:1536
	s_add_i32 s12, s10, 3
	s_lshl_b32 s13, s12, 11
	s_add_u32 s60, s30, 0x8ba0000
	s_addc_u32 s61, s31, 0
	s_add_u32 s60, s60, s13
	s_addc_u32 s61, s61, 0
	v_cvt_pk_f16_f32 v80, v80, v81
	v_cvt_pk_f16_f32 v81, v82, v83
	v_cvt_pk_f16_f32 v82, v84, v85
	v_cvt_pk_f16_f32 v83, v86, v87
	v_cvt_pk_f16_f32 v84, v88, v89
	v_cvt_pk_f16_f32 v85, v90, v91
	v_cvt_pk_f16_f32 v86, v92, v93
	v_cvt_pk_f16_f32 v87, v94, v95
	s_nop 0
	global_store_dwordx2 v5, v[80:81], s[60:61]
	global_store_dwordx2 v5, v[82:83], s[60:61] offset:512
	global_store_dwordx2 v5, v[84:85], s[60:61] offset:1024
	global_store_dwordx2 v5, v[86:87], s[60:61] offset:1536
	s_add_i32 s11, s11, 1
	s_add_i32 s10, s10, 4
	s_cmp_eq_u32 s11, 2
	s_cselect_b32 s10, s34, s10
	s_cmp_lt_u32 s11, s4
	s_cbranch_scc0 .Lrn0_done
	s_waitcnt vmcnt(0)
	s_branch .Lrn0_grp
.Lrn0_done:
	s_branch .LBB0_156
.LBB0_156:
	s_or_b64 exec, exec, s[6:7]
	s_waitcnt vmcnt(0)
	s_waitcnt lgkmcnt(0)
	s_barrier
	s_mov_b64 s[52:53], exec
	v_readlane_b32 s0, v238, 35
	v_readlane_b32 s1, v238, 36
	s_and_b64 s[0:1], s[52:53], s[0:1]
	v_writelane_b32 v238, s88, 38
	s_nop 1
	v_writelane_b32 v238, s89, 39
	s_mov_b64 exec, s[0:1]
	s_cbranch_execz .LBB0_208
	s_mov_b64 s[0:1], src_shared_base
	v_mov_b32_e32 v0, 0x13000
	v_mov_b32_e32 v1, s1
	s_waitcnt vmcnt(0) expcnt(0) lgkmcnt(0)
	flat_load_dword v2, v[0:1] sc0 sc1
	s_waitcnt vmcnt(0)
	v_mov_b32_e32 v0, 0x13004
	flat_load_dword v0, v[0:1] sc0 sc1
	s_waitcnt vmcnt(0) lgkmcnt(0)
	v_cmp_eq_u32_e32 vcc, 0, v2
	s_and_saveexec_b64 s[54:55], vcc
	s_cbranch_execz .LBB0_172
	s_add_u32 s0, s30, 0xf9c4200
	s_addc_u32 s1, s31, 0
	s_add_u32 s8, s30, 0xf9c4400
	s_addc_u32 s9, s31, 0
	s_add_u32 s10, s30, 0xf9c4500
	s_addc_u32 s11, s31, 0
	s_add_u32 s12, s30, 0xf9c4600
	s_addc_u32 s13, s31, 0
	s_add_u32 s14, s30, 0xf9c4700
	s_addc_u32 s15, s31, 0
	s_add_u32 s34, s30, 0xf9c4800
	s_addc_u32 s35, s31, 0
	s_add_u32 s50, s30, 0xf9c4900
	s_addc_u32 s51, s31, 0
	s_add_u32 s60, s30, 0xf9c4a00
	s_addc_u32 s61, s31, 0
	s_add_u32 s64, s30, 0xf9c4b00
	s_addc_u32 s65, s31, 0
	s_add_u32 s66, s30, 0xf9c4c00
	s_addc_u32 s67, s31, 0
	s_add_u32 s84, s30, 0xf9c4d00
	s_addc_u32 s85, s31, 0
	s_add_u32 s86, s30, 0xf9c4e00
	s_addc_u32 s87, s31, 0
	s_load_dwordx2 s[4:5], s[88:89], 0x108
	s_load_dword s3, s[88:89], 0x110
	s_add_u32 s88, s30, 0xf9c4f00
	s_addc_u32 s89, s31, 0
	s_add_u32 s90, s30, 0xf9c5000
	s_addc_u32 s91, s31, 0
	s_add_u32 s92, s30, 0xf9c5100
	s_addc_u32 s93, s31, 0
	s_add_u32 s94, s30, 0xf9c5200
	s_addc_u32 s95, s31, 0
	s_waitcnt lgkmcnt(0)
	s_mul_i32 s4, s5, s4
	s_add_u32 s96, s30, 0xf9c5300
	s_mul_i32 s3, s4, s3
	s_addc_u32 s97, s31, 0
	s_mov_b32 s33, 1
	v_mov_b32_e32 v16, 0
	s_branch .LBB0_160
